# v94: v93 + differential-head epilogue output stores paired into dwordx4 via v_permlane32_swap
# baseline (speedup 1.0000x reference)
; __device__ __forceinline__ float silu_f(float z) { return z * __builtin_amdgcn_rcpf(1.0f + __builtin_amdgcn_exp2f(-LOG2E * z)); }
; __device__ __forceinline__ float bf_lo(unsigned v) { return __uint_as_float(v << 16); }
; __device__ __forceinline__ float bf_hi(unsigned v) { return __uint_as_float(v & 0xffff0000u); }
; template <int MODE>
; __device__ __forceinline__ void attn_unit(const Params& P, LAS unsigned char* lds, const int b, const int h, const int qb) {
;     ...
;         if (mp == 0) {
;             const float lam = tab[TAB_LAM]; float ss = 0.f;
; #pragma unroll
;             for (int d = 0; d < 4; ++d)
; #pragma unroll
;                 for (int i = 0; i < 16; ++i) { const float o = O[d][i] * inv1 - lam * xb[((w * 4 + d) * 16 + i) * 64 + lane]; O[d][i] = o; ss += o * o; }
;     ...
;                 for (int a = 0; a < 4; ++a) { const int d0 = 32 * d + 8 * a + 4 * hh; const u32x2 z2 = zv[d][a]; const f32x4 g = gv[d][a];
;                     const float o0 = O[d][4 * a] * rstd * g[0] * silu_f(bf_lo(z2.x)), o1 = O[d][4 * a + 1] * rstd * g[1] * silu_f(bf_hi(z2.x));
;                     const float o2 = O[d][4 * a + 2] * rstd * g[2] * silu_f(bf_lo(z2.y)), o3 = O[d][4 * a + 3] * rstd * g[3] * silu_f(bf_hi(z2.y));
.LBB0_494:
	s_andn2_b64 vcc, exec, s[68:69]
	s_waitcnt lgkmcnt(0)
	s_barrier
	s_cbranch_vccnz .LBB0_496
	s_waitcnt vmcnt(0)
	v_permlane32_swap_b32 v240, v242
	v_permlane32_swap_b32 v241, v243
	v_mov_b32_e32 v170, v240
	v_mov_b32_e32 v171, v241
	v_mov_b32_e32 v160, v242
	v_mov_b32_e32 v161, v243
	v_permlane32_swap_b32 v244, v246
	v_permlane32_swap_b32 v245, v247
	v_mov_b32_e32 v158, v244
	v_mov_b32_e32 v159, v245
	v_mov_b32_e32 v168, v246
	v_mov_b32_e32 v169, v247
	v_permlane32_swap_b32 v154, v156
	v_permlane32_swap_b32 v155, v157
	v_permlane32_swap_b32 v248, v250
	v_permlane32_swap_b32 v249, v251
	v_mov_b32_e32 v146, v248
	v_mov_b32_e32 v147, v249
	v_mov_b32_e32 v152, v250
	v_mov_b32_e32 v153, v251
	v_permlane32_swap_b32 v142, v144
	v_permlane32_swap_b32 v143, v145
	v_permlane32_swap_b32 v138, v140
	v_permlane32_swap_b32 v139, v141
	v_permlane32_swap_b32 v134, v136
	v_permlane32_swap_b32 v135, v137
	v_permlane32_swap_b32 v184, v186
	v_permlane32_swap_b32 v185, v187
	v_mov_b32_e32 v14, v184
	v_mov_b32_e32 v15, v185
	v_mov_b32_e32 v132, v186
	v_mov_b32_e32 v133, v187
	global_load_dword v172, v1, s[62:63]
	v_lshlrev_b32_e32 v182, 16, v161
	v_lshlrev_b32_e32 v0, 12, v162
	v_mul_f32_e32 v162, 0xbfb8aa3b, v182
	s_lshl_b32 s0, s11, 14
	v_exp_f32_e32 v173, v162
	s_lshl_b64 s[68:69], s[12:13], 25
	v_lshlrev_b32_e32 v180, 16, v160
	v_and_b32_e32 v181, 0xffff0000, v160
	v_and_b32_e32 v183, 0xffff0000, v161
	v_lshl_add_u64 v[160:161], s[52:53], 0, v[0:1]
	s_addk_i32 s0, 0x100
	s_lshl_b32 s66, s96, 8
	s_mov_b32 s67, s13
	v_mul_f32_e32 v163, 0xbfb8aa3b, v183
	v_lshl_add_u64 v[160:161], v[160:161], 0, s[68:69]
	v_lshl_add_u32 v151, v151, 2, s0
	v_exp_f32_e32 v229, v163
	v_lshl_add_u64 v[226:227], v[160:161], 0, s[66:67]
	ds_read2st64_b32 v[160:161], v151 offset1:1
	ds_read2st64_b32 v[162:163], v151 offset0:2 offset1:3
	ds_read2st64_b32 v[164:165], v151 offset0:4 offset1:5
	ds_read2st64_b32 v[166:167], v151 offset0:6 offset1:7
	ds_read2st64_b32 v[174:175], v151 offset0:8 offset1:9
	ds_read2st64_b32 v[176:177], v151 offset0:10 offset1:11
	ds_read2st64_b32 v[192:193], v151 offset0:12 offset1:13
	ds_read2st64_b32 v[194:195], v151 offset0:14 offset1:15
	ds_read2st64_b32 v[222:223], v151 offset0:16 offset1:17
	ds_read2st64_b32 v[224:225], v151 offset0:18 offset1:19
	ds_read2st64_b32 v[210:211], v151 offset0:20 offset1:21
	ds_read2st64_b32 v[212:213], v151 offset0:22 offset1:23
	ds_read2st64_b32 v[202:203], v151 offset0:24 offset1:25
	ds_read2st64_b32 v[204:205], v151 offset0:26 offset1:27
	ds_read2st64_b32 v[188:189], v151 offset0:28 offset1:29
	ds_read2st64_b32 v[190:191], v151 offset0:30 offset1:31
	ds_read2st64_b32 v[218:219], v151 offset0:32 offset1:33
	ds_read2st64_b32 v[220:221], v151 offset0:34 offset1:35
	ds_read2st64_b32 v[214:215], v151 offset0:36 offset1:37
	ds_read2st64_b32 v[216:217], v151 offset0:38 offset1:39
	ds_read2st64_b32 v[206:207], v151 offset0:40 offset1:41
	ds_read2st64_b32 v[208:209], v151 offset0:42 offset1:43
	ds_read2st64_b32 v[198:199], v151 offset0:44 offset1:45
	ds_read2st64_b32 v[200:201], v151 offset0:46 offset1:47
	ds_read2st64_b32 v[184:185], v151 offset0:48 offset1:49
	ds_read2st64_b32 v[186:187], v151 offset0:50 offset1:51
	v_mul_f32_e32 v0, 0xbfb8aa3b, v180
	v_mul_f32_e32 v149, 0xbfb8aa3b, v181
	v_exp_f32_e32 v0, v0
	v_exp_f32_e32 v149, v149
	s_mov_b64 s[0:1], 0x4324800
	v_add_f32_e32 v0, 1.0, v0
	s_waitcnt vmcnt(0) lgkmcnt(14)
	v_pk_mul_f32 v[162:163], v[172:173], v[162:163] op_sel_hi:[0,1]
	v_pk_mul_f32 v[160:161], v[172:173], v[160:161] op_sel_hi:[0,1]
	v_pk_mul_f32 v[196:197], v[172:173], v[166:167] op_sel_hi:[0,1]
	v_pk_mul_f32 v[236:237], v[172:173], v[164:165] op_sel_hi:[0,1]
	v_pk_mul_f32 v[176:177], v[172:173], v[176:177] op_sel_hi:[0,1]
	v_pk_mul_f32 v[174:175], v[172:173], v[174:175] op_sel_hi:[0,1]
	v_pk_mul_f32 v[194:195], v[172:173], v[194:195] op_sel_hi:[0,1]
	v_pk_mul_f32 v[192:193], v[172:173], v[192:193] op_sel_hi:[0,1]
	v_pk_fma_f32 v[164:165], v[66:67], v[150:151], v[162:163] op_sel_hi:[1,0,1] neg_lo:[0,0,1] neg_hi:[0,0,1]
	v_pk_fma_f32 v[166:167], v[64:65], v[150:151], v[160:161] op_sel_hi:[1,0,1] neg_lo:[0,0,1] neg_hi:[0,0,1]
	v_pk_fma_f32 v[160:161], v[70:71], v[150:151], v[196:197] op_sel_hi:[1,0,1] neg_lo:[0,0,1] neg_hi:[0,0,1]
	v_pk_fma_f32 v[162:163], v[68:69], v[150:151], v[236:237] op_sel_hi:[1,0,1] neg_lo:[0,0,1] neg_hi:[0,0,1]
	v_pk_fma_f32 v[68:69], v[74:75], v[150:151], v[176:177] op_sel_hi:[1,0,1] neg_lo:[0,0,1] neg_hi:[0,0,1]
	v_pk_fma_f32 v[70:71], v[72:73], v[150:151], v[174:175] op_sel_hi:[1,0,1] neg_lo:[0,0,1] neg_hi:[0,0,1]
	v_pk_fma_f32 v[64:65], v[78:79], v[150:151], v[194:195] op_sel_hi:[1,0,1] neg_lo:[0,0,1] neg_hi:[0,0,1]
	v_pk_fma_f32 v[66:67], v[76:77], v[150:151], v[192:193] op_sel_hi:[1,0,1] neg_lo:[0,0,1] neg_hi:[0,0,1]
	ds_read2st64_b32 v[194:195], v151 offset0:52 offset1:53
	ds_read2st64_b32 v[196:197], v151 offset0:54 offset1:55
	ds_read2st64_b32 v[192:193], v151 offset0:56 offset1:57
	ds_read2st64_b32 v[72:73], v151 offset0:58 offset1:59
	ds_read2st64_b32 v[74:75], v151 offset0:60 offset1:61
	ds_read2st64_b32 v[76:77], v151 offset0:62 offset1:63
	v_add_f32_e32 v79, 1.0, v149
	v_add_f32_e32 v149, 1.0, v173
	v_rcp_f32_e32 v78, v0
	s_waitcnt lgkmcnt(2)
	v_pk_mul_f32 v[72:73], v[172:173], v[72:73] op_sel_hi:[0,1]
	s_waitcnt lgkmcnt(0)
; __device__ __forceinline__ float silu_f(float z) { return z * __builtin_amdgcn_rcpf(1.0f + __builtin_amdgcn_exp2f(-LOG2E * z)); }
; __device__ __forceinline__ float bf_lo(unsigned v) { return __uint_as_float(v << 16); }
; __device__ __forceinline__ float bf_hi(unsigned v) { return __uint_as_float(v & 0xffff0000u); }
; template <int MODE>
; __device__ __forceinline__ void attn_unit(const Params& P, LAS unsigned char* lds, const int b, const int h, const int qb) {
;     ...
;             for (int d = 0; d < 4; ++d)
; #pragma unroll
;                 for (int i = 0; i < 16; ++i) { const float o = O[d][i] * inv1 - lam * xb[((w * 4 + d) * 16 + i) * 64 + lane]; O[d][i] = o; ss += o * o; }
;             ss += __shfl_xor(ss, 32);
;             const float rstd = 0.8f * __builtin_amdgcn_rsqf(ss * (1.0f / 128.0f) + 1e-6f);
; #pragma unroll
;             for (int d = 0; d < 4; ++d)
; #pragma unroll
;                 for (int a = 0; a < 4; ++a) { const int d0 = 32 * d + 8 * a + 4 * hh; const u32x2 z2 = zv[d][a]; const f32x4 g = gv[d][a];
;                     const float o0 = O[d][4 * a] * rstd * g[0] * silu_f(bf_lo(z2.x)), o1 = O[d][4 * a + 1] * rstd * g[1] * silu_f(bf_hi(z2.x));
;                     const float o2 = O[d][4 * a + 2] * rstd * g[2] * silu_f(bf_lo(z2.y)), o3 = O[d][4 * a + 3] * rstd * g[3] * silu_f(bf_hi(z2.y));
	v_pk_mul_f32 v[76:77], v[172:173], v[76:77] op_sel_hi:[0,1]
	v_add_f32_e32 v0, 1.0, v229
	v_pk_fma_f32 v[72:73], v[26:27], v[150:151], v[72:73] op_sel_hi:[1,0,1] neg_lo:[0,0,1] neg_hi:[0,0,1]
	v_pk_fma_f32 v[26:27], v[30:31], v[150:151], v[76:77] op_sel_hi:[1,0,1] neg_lo:[0,0,1] neg_hi:[0,0,1]
	v_rcp_f32_e32 v30, v149
	v_rcp_f32_e32 v31, v0
	v_pk_mul_f32 v[74:75], v[172:173], v[74:75] op_sel_hi:[0,1]
	v_pk_fma_f32 v[28:29], v[28:29], v[150:151], v[74:75] op_sel_hi:[1,0,1] neg_lo:[0,0,1] neg_hi:[0,0,1]
	v_mov_b32_e32 v149, v1
	v_pk_mul_f32 v[76:77], v[30:31], v[182:183]
	v_pk_mul_f32 v[30:31], v[172:173], v[224:225] op_sel_hi:[0,1]
	v_pk_fma_f32 v[50:51], v[50:51], v[150:151], v[30:31] op_sel_hi:[1,0,1] neg_lo:[0,0,1] neg_hi:[0,0,1]
	v_pk_mul_f32 v[30:31], v[172:173], v[222:223] op_sel_hi:[0,1]
	v_pk_fma_f32 v[48:49], v[48:49], v[150:151], v[30:31] op_sel_hi:[1,0,1] neg_lo:[0,0,1] neg_hi:[0,0,1]
	v_pk_mul_f32 v[30:31], v[172:173], v[212:213] op_sel_hi:[0,1]
	v_pk_fma_f32 v[54:55], v[54:55], v[150:151], v[30:31] op_sel_hi:[1,0,1] neg_lo:[0,0,1] neg_hi:[0,0,1]
	v_pk_mul_f32 v[30:31], v[172:173], v[210:211] op_sel_hi:[0,1]
	v_pk_fma_f32 v[52:53], v[52:53], v[150:151], v[30:31] op_sel_hi:[1,0,1] neg_lo:[0,0,1] neg_hi:[0,0,1]
	v_pk_mul_f32 v[30:31], v[172:173], v[204:205] op_sel_hi:[0,1]
	v_pk_fma_f32 v[58:59], v[58:59], v[150:151], v[30:31] op_sel_hi:[1,0,1] neg_lo:[0,0,1] neg_hi:[0,0,1]
	v_pk_mul_f32 v[30:31], v[172:173], v[202:203] op_sel_hi:[0,1]
	v_pk_fma_f32 v[56:57], v[56:57], v[150:151], v[30:31] op_sel_hi:[1,0,1] neg_lo:[0,0,1] neg_hi:[0,0,1]
	v_pk_mul_f32 v[30:31], v[172:173], v[190:191] op_sel_hi:[0,1]
	v_pk_fma_f32 v[62:63], v[62:63], v[150:151], v[30:31] op_sel_hi:[1,0,1] neg_lo:[0,0,1] neg_hi:[0,0,1]
	v_pk_mul_f32 v[30:31], v[172:173], v[188:189] op_sel_hi:[0,1]
	v_lshlrev_b32_e32 v188, 16, v170
	v_and_b32_e32 v189, 0xffff0000, v170
	v_mul_f32_e32 v0, 0xbfb8aa3b, v188
	v_pk_fma_f32 v[60:61], v[60:61], v[150:151], v[30:31] op_sel_hi:[1,0,1] neg_lo:[0,0,1] neg_hi:[0,0,1]
	v_exp_f32_e32 v0, v0
	v_mul_f32_e32 v151, 0xbfb8aa3b, v189
	v_exp_f32_e32 v151, v151
	v_lshlrev_b32_e32 v210, 16, v171
	v_add_f32_e32 v0, 1.0, v0
	v_rcp_f32_e32 v190, v0
	v_add_f32_e32 v0, 1.0, v151
	v_rcp_f32_e32 v191, v0
	v_and_b32_e32 v211, 0xffff0000, v171
	v_mul_f32_e32 v0, 0xbfb8aa3b, v210
	v_exp_f32_e32 v0, v0
	v_mul_f32_e32 v151, 0xbfb8aa3b, v211
	v_exp_f32_e32 v151, v151
	v_pk_mul_f32 v[170:171], v[190:191], v[188:189]
	v_add_f32_e32 v0, 1.0, v0
	v_rcp_f32_e32 v188, v0
	v_add_f32_e32 v0, 1.0, v151
	v_lshlrev_b32_e32 v190, 16, v168
	v_rcp_f32_e32 v189, v0
	v_and_b32_e32 v191, 0xffff0000, v168
	v_mul_f32_e32 v0, 0xbfb8aa3b, v190
	v_exp_f32_e32 v0, v0
	v_mul_f32_e32 v151, 0xbfb8aa3b, v191
	v_exp_f32_e32 v151, v151
	v_lshlrev_b32_e32 v222, 16, v169
	v_add_f32_e32 v0, 1.0, v0
	v_rcp_f32_e32 v168, v0
	v_add_f32_e32 v0, 1.0, v151
	v_and_b32_e32 v223, 0xffff0000, v169
	v_mul_f32_e32 v151, 0xbfb8aa3b, v222
	v_exp_f32_e32 v151, v151
	v_mul_f32_e32 v169, 0xbfb8aa3b, v223
	v_exp_f32_e32 v173, v169
	v_rcp_f32_e32 v169, v0
	v_add_f32_e32 v0, 1.0, v151
	v_rcp_f32_e32 v224, v0
	v_add_f32_e32 v0, 1.0, v173
	v_rcp_f32_e32 v225, v0
	v_pk_mul_f32 v[190:191], v[168:169], v[190:191]
	v_pk_mul_f32 v[220:221], v[172:173], v[220:221] op_sel_hi:[0,1]
	v_pk_mul_f32 v[218:219], v[172:173], v[218:219] op_sel_hi:[0,1]
	v_pk_mul_f32 v[168:169], v[224:225], v[222:223]
	v_lshlrev_b32_e32 v222, 16, v158
	v_and_b32_e32 v223, 0xffff0000, v158
	v_mul_f32_e32 v0, 0xbfb8aa3b, v222
	v_pk_mul_f32 v[216:217], v[172:173], v[216:217] op_sel_hi:[0,1]
	v_pk_mul_f32 v[214:215], v[172:173], v[214:215] op_sel_hi:[0,1]
	v_pk_mul_f32 v[208:209], v[172:173], v[208:209] op_sel_hi:[0,1]
	v_pk_mul_f32 v[206:207], v[172:173], v[206:207] op_sel_hi:[0,1]
	v_pk_mul_f32 v[200:201], v[172:173], v[200:201] op_sel_hi:[0,1]
	v_pk_mul_f32 v[198:199], v[172:173], v[198:199] op_sel_hi:[0,1]
	v_exp_f32_e32 v0, v0
	v_pk_fma_f32 v[34:35], v[34:35], v[150:151], v[220:221] op_sel_hi:[1,0,1] neg_lo:[0,0,1] neg_hi:[0,0,1]
	v_pk_fma_f32 v[32:33], v[32:33], v[150:151], v[218:219] op_sel_hi:[1,0,1] neg_lo:[0,0,1] neg_hi:[0,0,1]
	v_pk_fma_f32 v[38:39], v[38:39], v[150:151], v[216:217] op_sel_hi:[1,0,1] neg_lo:[0,0,1] neg_hi:[0,0,1]
	v_pk_fma_f32 v[36:37], v[36:37], v[150:151], v[214:215] op_sel_hi:[1,0,1] neg_lo:[0,0,1] neg_hi:[0,0,1]
	v_pk_fma_f32 v[42:43], v[42:43], v[150:151], v[208:209] op_sel_hi:[1,0,1] neg_lo:[0,0,1] neg_hi:[0,0,1]
	v_pk_fma_f32 v[40:41], v[40:41], v[150:151], v[206:207] op_sel_hi:[1,0,1] neg_lo:[0,0,1] neg_hi:[0,0,1]
	v_pk_fma_f32 v[46:47], v[46:47], v[150:151], v[200:201] op_sel_hi:[1,0,1] neg_lo:[0,0,1] neg_hi:[0,0,1]
	v_pk_fma_f32 v[44:45], v[44:45], v[150:151], v[198:199] op_sel_hi:[1,0,1] neg_lo:[0,0,1] neg_hi:[0,0,1]
	v_mul_f32_e32 v151, 0xbfb8aa3b, v223
	v_exp_f32_e32 v151, v151
	v_add_f32_e32 v0, 1.0, v0
	v_rcp_f32_e32 v198, v0
	v_lshlrev_b32_e32 v200, 16, v159
	v_add_f32_e32 v0, 1.0, v151
	v_rcp_f32_e32 v199, v0
	v_and_b32_e32 v201, 0xffff0000, v159
	v_mul_f32_e32 v0, 0xbfb8aa3b, v200
	v_exp_f32_e32 v0, v0
	v_mul_f32_e32 v151, 0xbfb8aa3b, v201
	v_exp_f32_e32 v151, v151
	v_pk_mul_f32 v[158:159], v[198:199], v[222:223]
	v_add_f32_e32 v0, 1.0, v0
	v_rcp_f32_e32 v198, v0
	v_add_f32_e32 v0, 1.0, v151
	v_lshlrev_b32_e32 v216, 16, v156
	v_rcp_f32_e32 v199, v0
	v_mul_f32_e32 v0, 0xbfb8aa3b, v216
	v_and_b32_e32 v217, 0xffff0000, v156
	v_exp_f32_e32 v0, v0
	v_mul_f32_e32 v151, 0xbfb8aa3b, v217
	v_exp_f32_e32 v151, v151
	v_pk_mul_f32 v[198:199], v[198:199], v[200:201]
	v_add_f32_e32 v0, 1.0, v0
	v_lshlrev_b32_e32 v200, 16, v157
	v_rcp_f32_e32 v156, v0
	v_add_f32_e32 v0, 1.0, v151
	v_and_b32_e32 v201, 0xffff0000, v157
; __device__ __forceinline__ float silu_f(float z) { return z * __builtin_amdgcn_rcpf(1.0f + __builtin_amdgcn_exp2f(-LOG2E * z)); }
; __device__ __forceinline__ float bf_lo(unsigned v) { return __uint_as_float(v << 16); }
; __device__ __forceinline__ float bf_hi(unsigned v) { return __uint_as_float(v & 0xffff0000u); }
; template <int MODE>
; __device__ __forceinline__ void attn_unit(const Params& P, LAS unsigned char* lds, const int b, const int h, const int qb) {
;     ...
;             for (int d = 0; d < 4; ++d)
; #pragma unroll
;                 for (int i = 0; i < 16; ++i) { const float o = O[d][i] * inv1 - lam * xb[((w * 4 + d) * 16 + i) * 64 + lane]; O[d][i] = o; ss += o * o; }
;     ...
;                 for (int a = 0; a < 4; ++a) { const int d0 = 32 * d + 8 * a + 4 * hh; const u32x2 z2 = zv[d][a]; const f32x4 g = gv[d][a];
;                     const float o0 = O[d][4 * a] * rstd * g[0] * silu_f(bf_lo(z2.x)), o1 = O[d][4 * a + 1] * rstd * g[1] * silu_f(bf_hi(z2.x));
;                     const float o2 = O[d][4 * a + 2] * rstd * g[2] * silu_f(bf_lo(z2.y)), o3 = O[d][4 * a + 3] * rstd * g[3] * silu_f(bf_hi(z2.y));
	v_mul_f32_e32 v151, 0xbfb8aa3b, v200
	v_exp_f32_e32 v151, v151
	v_mul_f32_e32 v157, 0xbfb8aa3b, v201
	v_exp_f32_e32 v173, v157
	v_rcp_f32_e32 v157, v0
	v_add_f32_e32 v0, 1.0, v151
	v_rcp_f32_e32 v220, v0
	v_add_f32_e32 v0, 1.0, v173
	v_lshlrev_b32_e32 v222, 16, v154
	v_rcp_f32_e32 v221, v0
	v_and_b32_e32 v223, 0xffff0000, v154
	v_mul_f32_e32 v0, 0xbfb8aa3b, v222
	v_exp_f32_e32 v0, v0
	v_mul_f32_e32 v151, 0xbfb8aa3b, v223
	v_exp_f32_e32 v151, v151
	v_pk_mul_f32 v[200:201], v[220:221], v[200:201]
	v_add_f32_e32 v0, 1.0, v0
	v_rcp_f32_e32 v220, v0
	v_add_f32_e32 v0, 1.0, v151
	v_lshlrev_b32_e32 v224, 16, v155
	v_rcp_f32_e32 v221, v0
	v_and_b32_e32 v225, 0xffff0000, v155
	v_mul_f32_e32 v0, 0xbfb8aa3b, v224
	v_exp_f32_e32 v0, v0
	v_mul_f32_e32 v151, 0xbfb8aa3b, v225
	v_exp_f32_e32 v151, v151
	v_pk_mul_f32 v[184:185], v[172:173], v[184:185] op_sel_hi:[0,1]
	v_pk_mul_f32 v[192:193], v[172:173], v[192:193] op_sel_hi:[0,1]
	v_add_f32_e32 v0, 1.0, v0
	v_pk_mul_f32 v[154:155], v[220:221], v[222:223]
	v_rcp_f32_e32 v220, v0
	v_add_f32_e32 v0, 1.0, v151
	v_pk_fma_f32 v[184:185], v[16:17], v[150:151], v[184:185] op_sel_hi:[1,0,1] neg_lo:[0,0,1] neg_hi:[0,0,1]
	v_pk_fma_f32 v[16:17], v[24:25], v[150:151], v[192:193] op_sel_hi:[1,0,1] neg_lo:[0,0,1] neg_hi:[0,0,1]
	v_lshlrev_b32_e32 v24, 16, v152
	v_pk_mul_f32 v[186:187], v[172:173], v[186:187] op_sel_hi:[0,1]
	v_pk_mul_f32 v[196:197], v[172:173], v[196:197] op_sel_hi:[0,1]
	v_rcp_f32_e32 v221, v0
	v_and_b32_e32 v25, 0xffff0000, v152
	v_mul_f32_e32 v0, 0xbfb8aa3b, v24
	v_pk_mul_f32 v[194:195], v[172:173], v[194:195] op_sel_hi:[0,1]
	v_pk_fma_f32 v[172:173], v[18:19], v[150:151], v[186:187] op_sel_hi:[1,0,1] neg_lo:[0,0,1] neg_hi:[0,0,1]
	v_pk_fma_f32 v[18:19], v[22:23], v[150:151], v[196:197] op_sel_hi:[1,0,1] neg_lo:[0,0,1] neg_hi:[0,0,1]
	v_exp_f32_e32 v0, v0
	v_mul_f32_e32 v22, 0xbfb8aa3b, v25
	v_pk_fma_f32 v[20:21], v[20:21], v[150:151], v[194:195] op_sel_hi:[1,0,1] neg_lo:[0,0,1] neg_hi:[0,0,1]
	v_exp_f32_e32 v151, v22
	v_add_f32_e32 v0, 1.0, v0
	v_lshlrev_b32_e32 v152, 16, v153
	v_rcp_f32_e32 v150, v0
	v_add_f32_e32 v0, 1.0, v151
	v_and_b32_e32 v153, 0xffff0000, v153
	v_mul_f32_e32 v151, 0xbfb8aa3b, v152
	v_exp_f32_e32 v186, v151
	v_mul_f32_e32 v151, 0xbfb8aa3b, v153
	v_exp_f32_e32 v187, v151
	v_rcp_f32_e32 v151, v0
	v_add_f32_e32 v0, 1.0, v186
	v_rcp_f32_e32 v186, v0
	v_add_f32_e32 v0, 1.0, v187
	v_lshlrev_b32_e32 v192, 16, v146
	v_rcp_f32_e32 v187, v0
	v_and_b32_e32 v193, 0xffff0000, v146
	v_mul_f32_e32 v0, 0xbfb8aa3b, v192
	v_exp_f32_e32 v0, v0
	v_mul_f32_e32 v146, 0xbfb8aa3b, v193
	v_exp_f32_e32 v146, v146
	v_pk_mul_f32 v[24:25], v[150:151], v[24:25]
	v_add_f32_e32 v0, 1.0, v0
	v_pk_mul_f32 v[150:151], v[186:187], v[152:153]
	v_rcp_f32_e32 v152, v0
	v_add_f32_e32 v0, 1.0, v146
	v_lshlrev_b32_e32 v186, 16, v147
	v_rcp_f32_e32 v153, v0
	v_and_b32_e32 v187, 0xffff0000, v147
	v_mul_f32_e32 v0, 0xbfb8aa3b, v186
	v_exp_f32_e32 v0, v0
	v_mul_f32_e32 v146, 0xbfb8aa3b, v187
	v_exp_f32_e32 v194, v146
	v_pk_mul_f32 v[146:147], v[152:153], v[192:193]
	v_add_f32_e32 v0, 1.0, v0
	v_rcp_f32_e32 v152, v0
	v_add_f32_e32 v0, 1.0, v194
	v_lshlrev_b32_e32 v192, 16, v144
	v_rcp_f32_e32 v153, v0
	v_and_b32_e32 v193, 0xffff0000, v144
	v_mul_f32_e32 v0, 0xbfb8aa3b, v192
	v_exp_f32_e32 v0, v0
	v_mul_f32_e32 v144, 0xbfb8aa3b, v193
	v_exp_f32_e32 v144, v144
	v_pk_mul_f32 v[152:153], v[152:153], v[186:187]
	v_add_f32_e32 v0, 1.0, v0
	v_rcp_f32_e32 v186, v0
	v_add_f32_e32 v0, 1.0, v144
	v_lshlrev_b32_e32 v194, 16, v145
	v_rcp_f32_e32 v187, v0
	v_and_b32_e32 v195, 0xffff0000, v145
	v_mul_f32_e32 v0, 0xbfb8aa3b, v194
	v_exp_f32_e32 v0, v0
	v_mul_f32_e32 v144, 0xbfb8aa3b, v195
	v_exp_f32_e32 v196, v144
	v_pk_mul_f32 v[144:145], v[186:187], v[192:193]
	v_add_f32_e32 v0, 1.0, v0
	v_rcp_f32_e32 v186, v0
	v_add_f32_e32 v0, 1.0, v196
	v_lshlrev_b32_e32 v192, 16, v142
	v_rcp_f32_e32 v187, v0
	v_and_b32_e32 v193, 0xffff0000, v142
	v_mul_f32_e32 v0, 0xbfb8aa3b, v192
	v_exp_f32_e32 v0, v0
	v_mul_f32_e32 v142, 0xbfb8aa3b, v193
	v_exp_f32_e32 v142, v142
	v_pk_mul_f32 v[186:187], v[186:187], v[194:195]
	v_add_f32_e32 v0, 1.0, v0
	v_rcp_f32_e32 v194, v0
	v_add_f32_e32 v0, 1.0, v142
	v_lshlrev_b32_e32 v196, 16, v143
	v_rcp_f32_e32 v195, v0
	v_and_b32_e32 v197, 0xffff0000, v143
	v_mul_f32_e32 v0, 0xbfb8aa3b, v196
	v_exp_f32_e32 v0, v0
	v_mul_f32_e32 v142, 0xbfb8aa3b, v197
	v_pk_mul_f32 v[22:23], v[220:221], v[224:225]
	v_exp_f32_e32 v220, v142
	v_add_f32_e32 v0, 1.0, v0
	v_pk_mul_f32 v[142:143], v[194:195], v[192:193]
	v_rcp_f32_e32 v192, v0
	v_add_f32_e32 v0, 1.0, v220
	v_lshlrev_b32_e32 v194, 16, v140
	v_rcp_f32_e32 v193, v0
	v_and_b32_e32 v195, 0xffff0000, v140
	v_mul_f32_e32 v0, 0xbfb8aa3b, v194
	v_exp_f32_e32 v0, v0
	v_mul_f32_e32 v140, 0xbfb8aa3b, v195
	v_exp_f32_e32 v140, v140
	v_pk_mul_f32 v[192:193], v[192:193], v[196:197]
	v_add_f32_e32 v0, 1.0, v0
	v_rcp_f32_e32 v196, v0
	v_add_f32_e32 v0, 1.0, v140
	v_lshlrev_b32_e32 v220, 16, v141
	v_rcp_f32_e32 v197, v0
	v_and_b32_e32 v221, 0xffff0000, v141
	v_mul_f32_e32 v0, 0xbfb8aa3b, v220
	v_exp_f32_e32 v0, v0
	v_mul_f32_e32 v140, 0xbfb8aa3b, v221
	v_exp_f32_e32 v224, v140
	v_pk_mul_f32 v[140:141], v[196:197], v[194:195]
	v_add_f32_e32 v0, 1.0, v0
	v_rcp_f32_e32 v194, v0
	v_add_f32_e32 v0, 1.0, v224
	v_lshlrev_b32_e32 v196, 16, v138
	v_rcp_f32_e32 v195, v0
	v_and_b32_e32 v197, 0xffff0000, v138
	v_mul_f32_e32 v0, 0xbfb8aa3b, v196
	v_exp_f32_e32 v0, v0
	v_mul_f32_e32 v138, 0xbfb8aa3b, v197
	v_exp_f32_e32 v224, v138
	v_pk_mul_f32 v[194:195], v[194:195], v[220:221]
	v_lshlrev_b32_e32 v220, 16, v139
	v_add_f32_e32 v0, 1.0, v0
	v_and_b32_e32 v221, 0xffff0000, v139
	v_mul_f32_e32 v139, 0xbfb8aa3b, v220
; template <int MODE>
; __device__ __forceinline__ void attn_unit(const Params& P, LAS unsigned char* lds, const int b, const int h, const int qb) {
;     ...
;             for (int d = 0; d < 4; ++d)
; #pragma unroll
;                 for (int i = 0; i < 16; ++i) { const float o = O[d][i] * inv1 - lam * xb[((w * 4 + d) * 16 + i) * 64 + lane]; O[d][i] = o; ss += o * o; }
;             ss += __shfl_xor(ss, 32);
;             const float rstd = 0.8f * __builtin_amdgcn_rsqf(ss * (1.0f / 128.0f) + 1e-6f);
	v_rcp_f32_e32 v138, v0
	v_add_f32_e32 v0, 1.0, v224
	v_exp_f32_e32 v224, v139
	v_mul_f32_e32 v139, 0xbfb8aa3b, v221
	v_exp_f32_e32 v225, v139
	v_lshl_add_u64 v[74:75], v[226:227], 0, v[148:149]
	v_lshlrev_b32_e32 v226, 16, v136
	v_rcp_f32_e32 v139, v0
	v_add_f32_e32 v0, 1.0, v224
	v_and_b32_e32 v227, 0xffff0000, v136
	v_mul_f32_e32 v136, 0xbfb8aa3b, v226
	v_rcp_f32_e32 v224, v0
	v_add_f32_e32 v0, 1.0, v225
	v_exp_f32_e32 v136, v136
	v_mul_f32_e32 v225, 0xbfb8aa3b, v227
	v_exp_f32_e32 v229, v225
	v_rcp_f32_e32 v225, v0
	v_add_f32_e32 v0, 1.0, v136
	v_pk_mul_f32 v[148:149], v[166:167], v[166:167]
	v_rcp_f32_e32 v236, v0
	v_add_f32_e32 v0, 1.0, v229
	v_pk_mul_f32 v[182:183], v[164:165], v[164:165]
	v_rcp_f32_e32 v237, v0
	v_add_f32_e32 v0, v148, v149
	v_add_f32_e32 v0, v0, v182
	v_pk_mul_f32 v[204:205], v[162:163], v[162:163]
	v_add_f32_e32 v0, v0, v183
	v_add_f32_e32 v0, v0, v204
	v_pk_mul_f32 v[202:203], v[160:161], v[160:161]
	v_add_f32_e32 v0, v0, v205
	v_add_f32_e32 v0, v0, v202
	v_pk_mul_f32 v[212:213], v[70:71], v[70:71]
	v_add_f32_e32 v0, v0, v203
	v_add_f32_e32 v0, v0, v212
	v_pk_mul_f32 v[188:189], v[188:189], v[210:211]
	v_pk_mul_f32 v[210:211], v[68:69], v[68:69]
	v_add_f32_e32 v0, v0, v213
	v_add_f32_e32 v0, v0, v210
	v_pk_mul_f32 v[214:215], v[66:67], v[66:67]
	v_add_f32_e32 v0, v0, v211
	v_add_f32_e32 v0, v0, v214
	v_pk_mul_f32 v[206:207], v[64:65], v[64:65]
	v_add_f32_e32 v0, v0, v215
	v_add_f32_e32 v0, v0, v206
	v_pk_mul_f32 v[218:219], v[48:49], v[48:49]
	v_add_f32_e32 v0, v0, v207
	v_add_f32_e32 v0, v0, v218
	v_pk_mul_f32 v[208:209], v[50:51], v[50:51]
	v_add_f32_e32 v0, v0, v219
	v_add_f32_e32 v0, v0, v208
	v_pk_mul_f32 v[222:223], v[52:53], v[52:53]
	v_add_f32_e32 v0, v0, v209
	v_add_f32_e32 v0, v0, v222
	v_pk_mul_f32 v[156:157], v[156:157], v[216:217]
	v_pk_mul_f32 v[216:217], v[54:55], v[54:55]
	v_add_f32_e32 v0, v0, v223
	v_add_f32_e32 v0, v0, v216
	v_pk_mul_f32 v[196:197], v[138:139], v[196:197]
	v_pk_mul_f32 v[138:139], v[236:237], v[226:227]
	v_pk_mul_f32 v[226:227], v[56:57], v[56:57]
	v_add_f32_e32 v0, v0, v217
	v_add_f32_e32 v0, v0, v226
	v_pk_mul_f32 v[238:239], v[58:59], v[58:59]
	v_add_f32_e32 v0, v0, v227
	v_add_f32_e32 v0, v0, v238
	v_pk_mul_f32 v[182:183], v[60:61], v[60:61]
	v_add_f32_e32 v0, v0, v239
	v_add_f32_e32 v0, v0, v182
	v_pk_mul_f32 v[148:149], v[62:63], v[62:63]
	v_add_f32_e32 v0, v0, v183
	v_add_f32_e32 v0, v0, v148
	v_pk_mul_f32 v[202:203], v[32:33], v[32:33]
	v_add_f32_e32 v0, v0, v149
	v_add_f32_e32 v0, v0, v202
	v_pk_mul_f32 v[204:205], v[34:35], v[34:35]
	v_add_f32_e32 v0, v0, v203
	v_add_f32_e32 v0, v0, v204
	v_pk_mul_f32 v[210:211], v[36:37], v[36:37]
	v_add_f32_e32 v0, v0, v205
	v_add_f32_e32 v0, v0, v210
	v_pk_mul_f32 v[212:213], v[38:39], v[38:39]
	v_add_f32_e32 v0, v0, v211
	v_add_f32_e32 v0, v0, v212
	v_lshlrev_b32_e32 v136, 16, v137
	v_and_b32_e32 v137, 0xffff0000, v137
	v_pk_mul_f32 v[206:207], v[40:41], v[40:41]
	v_add_f32_e32 v0, v0, v213
	v_mul_f32_e32 v218, 0xbfb8aa3b, v136
	v_mul_f32_e32 v219, 0xbfb8aa3b, v137
	v_add_f32_e32 v0, v0, v206
	v_pk_mul_f32 v[214:215], v[42:43], v[42:43]
	v_exp_f32_e32 v218, v218
	v_exp_f32_e32 v219, v219
	v_add_f32_e32 v0, v0, v207
	v_add_f32_e32 v0, v0, v214
	v_pk_mul_f32 v[222:223], v[44:45], v[44:45]
	v_add_f32_e32 v0, v0, v215
	v_add_f32_e32 v0, v0, v222
	v_add_f32_e32 v208, 1.0, v218
	v_add_f32_e32 v209, 1.0, v219
	v_pk_mul_f32 v[218:219], v[46:47], v[46:47]
	v_add_f32_e32 v0, v0, v223
	v_add_f32_e32 v0, v0, v218
	v_pk_mul_f32 v[236:237], v[184:185], v[184:185]
	v_add_f32_e32 v0, v0, v219
	v_add_f32_e32 v0, v0, v236
	v_pk_mul_f32 v[226:227], v[172:173], v[172:173]
	v_add_f32_e32 v0, v0, v237
	v_add_f32_e32 v0, v0, v226
	v_pk_mul_f32 v[148:149], v[20:21], v[20:21]
	v_add_f32_e32 v0, v0, v227
	v_pk_mul_f32 v[220:221], v[224:225], v[220:221]
	v_lshlrev_b32_e32 v224, 16, v134
	v_and_b32_e32 v225, 0xffff0000, v134
	v_lshlrev_b32_e32 v134, 16, v135
	v_add_f32_e32 v0, v0, v148
	v_and_b32_e32 v135, 0xffff0000, v135
	v_pk_mul_f32 v[182:183], v[18:19], v[18:19]
	v_mul_f32_e32 v202, 0xbfb8aa3b, v134
	v_add_f32_e32 v0, v0, v149
	v_exp_f32_e32 v229, v202
	v_mul_f32_e32 v202, 0xbfb8aa3b, v135
	v_add_f32_e32 v0, v0, v182
	v_exp_f32_e32 v238, v202
	v_pk_mul_f32 v[202:203], v[16:17], v[16:17]
	v_add_f32_e32 v0, v0, v183
	v_add_f32_e32 v0, v0, v202
	v_rcp_f32_e32 v79, v79
	v_pk_mul_f32 v[174:175], v[72:73], v[72:73]
	v_add_f32_e32 v0, v0, v203
	v_add_f32_e32 v0, v0, v174
	v_pk_mul_f32 v[176:177], v[28:29], v[28:29]
	v_add_f32_e32 v0, v0, v175
	v_add_f32_e32 v0, v0, v176
	v_pk_mul_f32 v[78:79], v[78:79], v[180:181]
	v_pk_mul_f32 v[180:181], v[26:27], v[26:27]
	v_add_f32_e32 v0, v0, v177
	v_add_f32_e32 v0, v0, v180
	v_add_f32_e32 v0, v0, v181
	ds_bpermute_b32 v174, v228, v0
	v_mul_f32_e32 v216, 0xbfb8aa3b, v224
	v_mul_f32_e32 v217, 0xbfb8aa3b, v225
	v_exp_f32_e32 v216, v216
	v_exp_f32_e32 v217, v217
	s_waitcnt lgkmcnt(0)
; __device__ __forceinline__ float silu_f(float z) { return z * __builtin_amdgcn_rcpf(1.0f + __builtin_amdgcn_exp2f(-LOG2E * z)); }
; __device__ __forceinline__ float bf_lo(unsigned v) { return __uint_as_float(v << 16); }
; __device__ __forceinline__ float bf_hi(unsigned v) { return __uint_as_float(v & 0xffff0000u); }
; template <int MODE>
; __device__ __forceinline__ void attn_unit(const Params& P, LAS unsigned char* lds, const int b, const int h, const int qb) {
;     ...
;             const float rstd = 0.8f * __builtin_amdgcn_rsqf(ss * (1.0f / 128.0f) + 1e-6f);
; #pragma unroll
;             for (int d = 0; d < 4; ++d)
; #pragma unroll
;                 for (int a = 0; a < 4; ++a) { const int d0 = 32 * d + 8 * a + 4 * hh; const u32x2 z2 = zv[d][a]; const f32x4 g = gv[d][a];
;                     const float o0 = O[d][4 * a] * rstd * g[0] * silu_f(bf_lo(z2.x)), o1 = O[d][4 * a + 1] * rstd * g[1] * silu_f(bf_hi(z2.x));
;                     const float o2 = O[d][4 * a + 2] * rstd * g[2] * silu_f(bf_lo(z2.y)), o3 = O[d][4 * a + 3] * rstd * g[3] * silu_f(bf_hi(z2.y));
;                     u32x2 ov; ov.x = cvt_pk_bf16(o0, o1); ov.y = cvt_pk_bf16(o2, o3); *(u32x2*)(mix + d0) = ov; }
	v_add_f32_e32 v0, v0, v174
	v_fmamk_f32 v0, v0, 0x3c000000, v230
	v_rsq_f32_e32 v0, v0
	v_add_f32_e32 v216, 1.0, v216
	v_add_f32_e32 v217, 1.0, v217
	v_rcp_f32_e32 v216, v216
	v_rcp_f32_e32 v217, v217
	v_add_f32_e32 v148, 1.0, v229
	v_add_f32_e32 v149, 1.0, v238
	v_rcp_f32_e32 v148, v148
	v_rcp_f32_e32 v149, v149
	v_mul_f32_e32 v0, 0x3f4ccccd, v0
	v_pk_mul_f32 v[20:21], v[20:21], v[0:1] op_sel_hi:[1,0]
	v_pk_mul_f32 v[174:175], v[216:217], v[224:225]
	v_pk_mul_f32 v[10:11], v[10:11], v[20:21]
	v_pk_mul_f32 v[18:19], v[18:19], v[0:1] op_sel_hi:[1,0]
	v_pk_mul_f32 v[134:135], v[148:149], v[134:135]
	v_pk_mul_f32 v[48:49], v[48:49], v[0:1] op_sel_hi:[1,0]
	v_pk_mul_f32 v[50:51], v[50:51], v[0:1] op_sel_hi:[1,0]
	v_pk_mul_f32 v[10:11], v[174:175], v[10:11]
	v_pk_mul_f32 v[12:13], v[12:13], v[18:19]
	v_lshlrev_b32_e32 v18, 16, v132
	v_pk_mul_f32 v[48:49], v[112:113], v[48:49]
	v_pk_mul_f32 v[50:51], v[114:115], v[50:51]
	v_pk_mul_f32 v[12:13], v[134:135], v[12:13]
	v_cvt_pk_bf16_f32 v10, v10, v11
	v_mul_f32_e32 v11, 0xbfb8aa3b, v18
	v_lshl_add_u64 v[30:31], v[74:75], 0, s[0:1]
	v_and_b32_e32 v250, 32, v178
	v_lshrrev_b32_e32 v250, 2, v250
	v_mov_b32_e32 v251, 0
	v_lshl_add_u64 v[30:31], v[30:31], 0, v[250:251]
	v_pk_mul_f32 v[48:49], v[156:157], v[48:49]
	v_pk_mul_f32 v[50:51], v[200:201], v[50:51]
	v_exp_f32_e32 v20, v11
	v_cvt_pk_bf16_f32 v11, v12, v13
	v_and_b32_e32 v19, 0xffff0000, v132
	v_cvt_pk_bf16_f32 v48, v48, v49
	v_cvt_pk_bf16_f32 v49, v50, v51
	v_mov_b32_e32 v240, v10
	v_mov_b32_e32 v241, v11
	v_mul_f32_e32 v11, 0xbfb8aa3b, v19
	v_pk_mul_f32 v[12:13], v[16:17], v[0:1] op_sel_hi:[1,0]
	v_mov_b32_e32 v242, v48
	v_mov_b32_e32 v243, v49
	v_pk_mul_f32 v[48:49], v[52:53], v[0:1] op_sel_hi:[1,0]
	v_pk_mul_f32 v[50:51], v[54:55], v[0:1] op_sel_hi:[1,0]
	v_exp_f32_e32 v11, v11
	v_pk_mul_f32 v[6:7], v[6:7], v[12:13]
	v_lshlrev_b32_e32 v12, 16, v133
	v_and_b32_e32 v13, 0xffff0000, v133
	v_pk_mul_f32 v[48:49], v[108:109], v[48:49]
	v_pk_mul_f32 v[50:51], v[110:111], v[50:51]
	v_mul_f32_e32 v16, 0xbfb8aa3b, v12
	v_mul_f32_e32 v17, 0xbfb8aa3b, v13
	v_pk_mul_f32 v[48:49], v[154:155], v[48:49]
	v_pk_mul_f32 v[22:23], v[22:23], v[50:51]
	v_exp_f32_e32 v16, v16
	v_exp_f32_e32 v17, v17
	v_cvt_pk_bf16_f32 v48, v48, v49
	v_cvt_pk_bf16_f32 v49, v22, v23
	v_pk_mul_f32 v[22:23], v[56:57], v[0:1] op_sel_hi:[1,0]
	v_add_f32_e32 v10, 1.0, v20
	v_pk_mul_f32 v[22:23], v[104:105], v[22:23]
	v_add_f32_e32 v11, 1.0, v11
	v_pk_mul_f32 v[22:23], v[24:25], v[22:23]
	v_pk_mul_f32 v[24:25], v[58:59], v[0:1] op_sel_hi:[1,0]
	v_rcp_f32_e32 v10, v10
	v_rcp_f32_e32 v11, v11
	v_pk_mul_f32 v[24:25], v[106:107], v[24:25]
	v_add_f32_e32 v16, 1.0, v16
	v_add_f32_e32 v17, 1.0, v17
	v_pk_mul_f32 v[24:25], v[150:151], v[24:25]
	v_rcp_f32_e32 v16, v16
	v_rcp_f32_e32 v17, v17
	v_cvt_pk_bf16_f32 v22, v22, v23
	v_cvt_pk_bf16_f32 v23, v24, v25
	v_mov_b32_e32 v244, v22
	v_mov_b32_e32 v245, v23
	v_pk_mul_f32 v[22:23], v[60:61], v[0:1] op_sel_hi:[1,0]
	v_pk_mul_f32 v[24:25], v[62:63], v[0:1] op_sel_hi:[1,0]
	v_pk_mul_f32 v[10:11], v[10:11], v[18:19]
	v_pk_mul_f32 v[22:23], v[100:101], v[22:23]
	v_pk_mul_f32 v[24:25], v[102:103], v[24:25]
	v_pk_mul_f32 v[6:7], v[10:11], v[6:7]
	v_pk_mul_f32 v[10:11], v[72:73], v[0:1] op_sel_hi:[1,0]
	v_pk_mul_f32 v[22:23], v[146:147], v[22:23]
	v_pk_mul_f32 v[24:25], v[152:153], v[24:25]
	v_pk_mul_f32 v[8:9], v[8:9], v[10:11]
	v_pk_mul_f32 v[10:11], v[16:17], v[12:13]
	v_cvt_pk_bf16_f32 v22, v22, v23
	v_cvt_pk_bf16_f32 v23, v24, v25
	v_pk_mul_f32 v[8:9], v[10:11], v[8:9]
	v_lshlrev_b32_e32 v10, 16, v14
	v_mov_b32_e32 v250, v244
	v_mov_b32_e32 v251, v245
	v_mov_b32_e32 v252, v22
	v_mov_b32_e32 v253, v23
	s_nop 1
	v_permlane32_swap_b32 v250, v252
	v_permlane32_swap_b32 v251, v253
	global_store_dwordx4 v[30:31], v[250:253], off offset:96
	s_nop 1
	v_pk_mul_f32 v[22:23], v[32:33], v[0:1] op_sel_hi:[1,0]
	v_pk_mul_f32 v[24:25], v[34:35], v[0:1] op_sel_hi:[1,0]
	v_cvt_pk_bf16_f32 v6, v6, v7
	v_mul_f32_e32 v7, 0xbfb8aa3b, v10
	v_pk_mul_f32 v[22:23], v[96:97], v[22:23]
	v_pk_mul_f32 v[24:25], v[98:99], v[24:25]
	v_exp_f32_e32 v12, v7
	v_cvt_pk_bf16_f32 v7, v8, v9
	v_and_b32_e32 v11, 0xffff0000, v14
	v_pk_mul_f32 v[22:23], v[144:145], v[22:23]
	v_pk_mul_f32 v[24:25], v[186:187], v[24:25]
	v_mov_b32_e32 v244, v6
	v_mov_b32_e32 v245, v7
	v_mul_f32_e32 v7, 0xbfb8aa3b, v11
	v_cvt_pk_bf16_f32 v22, v22, v23
	v_cvt_pk_bf16_f32 v23, v24, v25
	v_exp_f32_e32 v7, v7
	v_mov_b32_e32 v246, v22
	v_mov_b32_e32 v247, v23
	v_pk_mul_f32 v[22:23], v[36:37], v[0:1] op_sel_hi:[1,0]
	v_pk_mul_f32 v[24:25], v[38:39], v[0:1] op_sel_hi:[1,0]
	v_pk_mul_f32 v[22:23], v[92:93], v[22:23]
	v_pk_mul_f32 v[24:25], v[94:95], v[24:25]
	v_pk_mul_f32 v[8:9], v[28:29], v[0:1] op_sel_hi:[1,0]
	v_pk_mul_f32 v[22:23], v[142:143], v[22:23]
	v_pk_mul_f32 v[24:25], v[192:193], v[24:25]
	v_pk_mul_f32 v[2:3], v[2:3], v[8:9]
	v_lshlrev_b32_e32 v8, 16, v15
	v_and_b32_e32 v9, 0xffff0000, v15
	v_cvt_pk_bf16_f32 v22, v22, v23
	v_cvt_pk_bf16_f32 v23, v24, v25
	v_add_f32_e32 v6, 1.0, v12
	v_add_f32_e32 v7, 1.0, v7
	v_mul_f32_e32 v12, 0xbfb8aa3b, v8
	v_mul_f32_e32 v13, 0xbfb8aa3b, v9
; __device__ __forceinline__ float silu_f(float z) { return z * __builtin_amdgcn_rcpf(1.0f + __builtin_amdgcn_exp2f(-LOG2E * z)); }
; __device__ __forceinline__ float bf_lo(unsigned v) { return __uint_as_float(v << 16); }
; __device__ __forceinline__ float bf_hi(unsigned v) { return __uint_as_float(v & 0xffff0000u); }
; template <int MODE>
; __device__ __forceinline__ void attn_unit(const Params& P, LAS unsigned char* lds, const int b, const int h, const int qb) {
;     ...
;             for (int d = 0; d < 4; ++d)
; #pragma unroll
;                 for (int a = 0; a < 4; ++a) { const int d0 = 32 * d + 8 * a + 4 * hh; const u32x2 z2 = zv[d][a]; const f32x4 g = gv[d][a];
;                     const float o0 = O[d][4 * a] * rstd * g[0] * silu_f(bf_lo(z2.x)), o1 = O[d][4 * a + 1] * rstd * g[1] * silu_f(bf_hi(z2.x));
;                     const float o2 = O[d][4 * a + 2] * rstd * g[2] * silu_f(bf_lo(z2.y)), o3 = O[d][4 * a + 3] * rstd * g[3] * silu_f(bf_hi(z2.y));
;                     u32x2 ov; ov.x = cvt_pk_bf16(o0, o1); ov.y = cvt_pk_bf16(o2, o3); *(u32x2*)(mix + d0) = ov; }
	v_mov_b32_e32 v250, v246
	v_mov_b32_e32 v251, v247
	v_mov_b32_e32 v252, v22
	v_mov_b32_e32 v253, v23
	s_nop 1
	v_permlane32_swap_b32 v250, v252
	v_permlane32_swap_b32 v251, v253
	global_store_dwordx4 v[30:31], v[250:253], off offset:128
	s_nop 1
	v_pk_mul_f32 v[22:23], v[40:41], v[0:1] op_sel_hi:[1,0]
	v_pk_mul_f32 v[24:25], v[42:43], v[0:1] op_sel_hi:[1,0]
	v_rcp_f32_e32 v6, v6
	v_rcp_f32_e32 v7, v7
	v_exp_f32_e32 v12, v12
	v_exp_f32_e32 v13, v13
	v_pk_mul_f32 v[22:23], v[88:89], v[22:23]
	v_pk_mul_f32 v[24:25], v[90:91], v[24:25]
	v_pk_mul_f32 v[148:149], v[166:167], v[0:1] op_sel_hi:[1,0]
	v_pk_mul_f32 v[22:23], v[140:141], v[22:23]
	v_pk_mul_f32 v[24:25], v[194:195], v[24:25]
	v_pk_mul_f32 v[128:129], v[128:129], v[148:149]
	v_cvt_pk_bf16_f32 v22, v22, v23
	v_cvt_pk_bf16_f32 v23, v24, v25
	v_pk_mul_f32 v[78:79], v[78:79], v[128:129]
	v_pk_mul_f32 v[128:129], v[164:165], v[0:1] op_sel_hi:[1,0]
	v_mov_b32_e32 v246, v22
	v_mov_b32_e32 v247, v23
	v_pk_mul_f32 v[22:23], v[44:45], v[0:1] op_sel_hi:[1,0]
	v_pk_mul_f32 v[24:25], v[46:47], v[0:1] op_sel_hi:[1,0]
	v_pk_mul_f32 v[6:7], v[6:7], v[10:11]
	v_add_f32_e32 v10, 1.0, v12
	v_add_f32_e32 v11, 1.0, v13
	v_rcp_f32_e32 v208, v208
	v_rcp_f32_e32 v209, v209
	v_pk_mul_f32 v[128:129], v[130:131], v[128:129]
	s_mov_b32 s0, 0x4324000
	v_pk_mul_f32 v[22:23], v[84:85], v[22:23]
	v_pk_mul_f32 v[24:25], v[86:87], v[24:25]
	v_rcp_f32_e32 v10, v10
	v_rcp_f32_e32 v11, v11
	v_pk_mul_f32 v[76:77], v[76:77], v[128:129]
	v_add_co_u32_e32 v74, vcc, s0, v74
	v_pk_mul_f32 v[22:23], v[196:197], v[22:23]
	v_pk_mul_f32 v[24:25], v[220:221], v[24:25]
	v_cvt_pk_bf16_f32 v78, v78, v79
	v_cvt_pk_bf16_f32 v79, v76, v77
	v_addc_co_u32_e32 v75, vcc, 0, v75, vcc
	v_cvt_pk_bf16_f32 v22, v22, v23
	v_cvt_pk_bf16_f32 v23, v24, v25
	v_mov_b32_e32 v248, v78
	v_mov_b32_e32 v249, v79
	v_pk_mul_f32 v[74:75], v[162:163], v[0:1] op_sel_hi:[1,0]
	v_pk_mul_f32 v[76:77], v[160:161], v[0:1] op_sel_hi:[1,0]
	v_pk_mul_f32 v[70:71], v[70:71], v[0:1] op_sel_hi:[1,0]
	v_pk_mul_f32 v[68:69], v[68:69], v[0:1] op_sel_hi:[1,0]
	v_pk_mul_f32 v[66:67], v[66:67], v[0:1] op_sel_hi:[1,0]
	v_pk_mul_f32 v[64:65], v[64:65], v[0:1] op_sel_hi:[1,0]
	v_mov_b32_e32 v250, v246
	v_mov_b32_e32 v251, v247
	v_mov_b32_e32 v252, v22
	v_mov_b32_e32 v253, v23
	s_nop 1
	v_permlane32_swap_b32 v250, v252
	v_permlane32_swap_b32 v251, v253
	global_store_dwordx4 v[30:31], v[250:253], off offset:160
	s_nop 1
	v_pk_mul_f32 v[22:23], v[184:185], v[0:1] op_sel_hi:[1,0]
	v_pk_mul_f32 v[24:25], v[172:173], v[0:1] op_sel_hi:[1,0]
	v_pk_mul_f32 v[2:3], v[6:7], v[2:3]
	v_pk_mul_f32 v[6:7], v[26:27], v[0:1] op_sel_hi:[1,0]
	v_pk_mul_f32 v[136:137], v[208:209], v[136:137]
	v_pk_mul_f32 v[74:75], v[124:125], v[74:75]
	v_pk_mul_f32 v[76:77], v[126:127], v[76:77]
	v_pk_mul_f32 v[70:71], v[120:121], v[70:71]
	v_pk_mul_f32 v[68:69], v[122:123], v[68:69]
	v_pk_mul_f32 v[66:67], v[116:117], v[66:67]
	v_pk_mul_f32 v[64:65], v[118:119], v[64:65]
	v_pk_mul_f32 v[22:23], v[80:81], v[22:23]
	v_pk_mul_f32 v[24:25], v[82:83], v[24:25]
	v_pk_mul_f32 v[4:5], v[4:5], v[6:7]
	v_pk_mul_f32 v[6:7], v[10:11], v[8:9]
	v_pk_mul_f32 v[74:75], v[170:171], v[74:75]
	v_pk_mul_f32 v[76:77], v[188:189], v[76:77]
	v_pk_mul_f32 v[70:71], v[190:191], v[70:71]
	v_pk_mul_f32 v[68:69], v[168:169], v[68:69]
	v_pk_mul_f32 v[66:67], v[158:159], v[66:67]
	v_pk_mul_f32 v[64:65], v[198:199], v[64:65]
	v_pk_mul_f32 v[22:23], v[138:139], v[22:23]
	v_pk_mul_f32 v[24:25], v[136:137], v[24:25]
	v_pk_mul_f32 v[4:5], v[6:7], v[4:5]
	v_cvt_pk_bf16_f32 v74, v74, v75
	v_cvt_pk_bf16_f32 v75, v76, v77
	v_cvt_pk_bf16_f32 v70, v70, v71
	v_cvt_pk_bf16_f32 v71, v68, v69
	v_cvt_pk_bf16_f32 v66, v66, v67
	v_cvt_pk_bf16_f32 v67, v64, v65
	v_cvt_pk_bf16_f32 v22, v22, v23
	v_cvt_pk_bf16_f32 v23, v24, v25
	v_cvt_pk_bf16_f32 v2, v2, v3
	v_cvt_pk_bf16_f32 v3, v4, v5
	v_mov_b32_e32 v250, v248
	v_mov_b32_e32 v251, v249
	v_mov_b32_e32 v252, v74
	v_mov_b32_e32 v253, v75
	s_nop 1
	v_permlane32_swap_b32 v250, v252
	v_permlane32_swap_b32 v251, v253
	global_store_dwordx4 v[30:31], v[250:253], off
	s_nop 1
	v_mov_b32_e32 v246, v70
	v_mov_b32_e32 v247, v71
	v_mov_b32_e32 v250, v246
	v_mov_b32_e32 v251, v247
	v_mov_b32_e32 v252, v66
	v_mov_b32_e32 v253, v67
	s_nop 1
	v_permlane32_swap_b32 v250, v252
	v_permlane32_swap_b32 v251, v253
	global_store_dwordx4 v[30:31], v[250:253], off offset:32
	s_nop 1
	v_mov_b32_e32 v250, v242
	v_mov_b32_e32 v251, v243
	v_mov_b32_e32 v252, v48
	v_mov_b32_e32 v253, v49
	s_nop 1
	v_permlane32_swap_b32 v250, v252
	v_permlane32_swap_b32 v251, v253
	global_store_dwordx4 v[30:31], v[250:253], off offset:64
	s_nop 1
	v_mov_b32_e32 v250, v22
	v_mov_b32_e32 v251, v23
	v_mov_b32_e32 v252, v240
	v_mov_b32_e32 v253, v241
	s_nop 1
	v_permlane32_swap_b32 v250, v252
	v_permlane32_swap_b32 v251, v253
	global_store_dwordx4 v[30:31], v[250:253], off offset:192
	s_nop 1
	v_mov_b32_e32 v250, v244
	v_mov_b32_e32 v251, v245
	v_mov_b32_e32 v252, v2
	v_mov_b32_e32 v253, v3
	s_nop 1
	v_permlane32_swap_b32 v250, v252
	v_permlane32_swap_b32 v251, v253
	global_store_dwordx4 v[30:31], v[250:253], off offset:224
	s_nop 1
